# phase-0 weight transposes: 16 row loads per thread issued together (was one waited load at a time); plus filter MLP load batching, GEMM ring loops, conv d-loop, hyena post/pre fast paths
# speedup vs baseline: 1.1619x; 1.0221x over previous
; DI int tidx() { return tid512() & 255; }
; DI void transpose_tile(const float* __restrict__ src, bf16_t* __restrict__ dst, int K, int N, const float* kscale, int mode, int tile, char* smem) {
;   float* sm = (float*)smem;
;   const int ntn = (N + 63) >> 6;
;   const int tk = tile / ntn, tn = tile - tk * ntn, k0 = tk * 64, n0 = tn * 64, tid = tidx();
;   __syncthreads();
; #pragma unroll 4
;   for (int i = 0; i < 16; ++i) {
;     int k = (tid >> 6) + 4 * i, n = n0 + (tid & 63);
;     float v = (n < N) ? src[(size_t)(k0 + k) * N + n] : 0.f;
;     if (kscale) v *= kscale[k0 + k];
;     sm[k * 65 + (tid & 63)] = v;
;   }
;   __syncthreads();
.LBB0_112:
	s_add_i32 s6, s49, 63
	s_lshr_b32 s6, s6, 6
	v_cvt_f32_ubyte0_e32 v2, s6
	v_rcp_iflag_f32_e32 v2, v2
	s_sub_i32 s36, 0, s6
	s_abs_i32 s7, s44
	s_ashr_i32 s46, s44, 31
	v_mul_f32_e32 v2, 0x4f7ffffe, v2
	v_cvt_u32_f32_e32 v2, v2
	v_mov_b32_e32 v9, v196
	s_mov_b32 s68, 0
	v_readfirstlane_b32 s42, v2
	s_mul_i32 s36, s36, s42
	s_mul_hi_u32 s36, s42, s36
	s_add_i32 s42, s42, s36
	s_mul_hi_u32 s36, s7, s42
	s_mul_i32 s42, s36, s6
	s_sub_i32 s7, s7, s42
	s_add_i32 s43, s36, 1
	s_sub_i32 s42, s7, s6
	s_cmp_ge_u32 s7, s6
	s_cselect_b32 s36, s43, s36
	s_cselect_b32 s7, s42, s7
	s_add_i32 s42, s36, 1
	s_cmp_ge_u32 s7, s6
	s_cselect_b32 s7, s42, s36
	s_xor_b32 s47, s7, s46
	s_sub_i32 s7, s47, s46
	s_mul_i32 s6, s7, s6
	s_sub_i32 s69, s44, s6
	s_lshl_b32 s42, s7, 6
	s_lshl_b32 s36, s69, 6
	v_and_b32_e32 v7, 63, v9
	s_cmp_lg_u64 s[12:13], 0
	v_bfe_u32 v6, v9, 6, 2
	v_or_b32_e32 v2, s36, v7
	s_cselect_b64 s[44:45], -1, 0
	s_ashr_i32 s43, s42, 31
	v_ashrrev_i32_e32 v3, 31, v2
	v_or_b32_e32 v4, s42, v6
	v_mov_b32_e32 v5, s43
	v_cmp_gt_i32_e64 s[6:7], s49, v2
	v_lshl_add_u64 v[2:3], v[2:3], 2, s[8:9]
	v_mul_u32_u24_e32 v10, 0x104, v6
	v_lshlrev_b32_e32 v7, 2, v7
	v_lshl_or_b32 v6, s47, 6, v6
	s_lshl_b32 s8, s46, 6
	v_lshl_add_u64 v[4:5], v[4:5], 2, s[12:13]
	v_add3_u32 v10, v10, v7, s51
	v_subrev_u32_e32 v11, s8, v6
	v_lshl_add_u64 v[4:5], v[4:5], 0, 32
	s_barrier
	v_mad_i64_i32 v[80:81], s[46:47], v11, s49, 0
	s_lshl_b32 s2, s49, 4
	s_mov_b32 s3, 0
	v_lshl_add_u64 v[80:81], v[80:81], 2, v[2:3]
	v_lshl_add_u64 v[82:83], v[80:81], 0, s[2:3]
	v_lshl_add_u64 v[84:85], v[82:83], 0, s[2:3]
	v_lshl_add_u64 v[86:87], v[84:85], 0, s[2:3]
	v_lshl_add_u64 v[88:89], v[86:87], 0, s[2:3]
	v_lshl_add_u64 v[90:91], v[88:89], 0, s[2:3]
	v_lshl_add_u64 v[92:93], v[90:91], 0, s[2:3]
	v_lshl_add_u64 v[94:95], v[92:93], 0, s[2:3]
	v_lshl_add_u64 v[96:97], v[94:95], 0, s[2:3]
	v_lshl_add_u64 v[98:99], v[96:97], 0, s[2:3]
	v_lshl_add_u64 v[100:101], v[98:99], 0, s[2:3]
	v_lshl_add_u64 v[102:103], v[100:101], 0, s[2:3]
	v_lshl_add_u64 v[104:105], v[102:103], 0, s[2:3]
	v_lshl_add_u64 v[106:107], v[104:105], 0, s[2:3]
	v_lshl_add_u64 v[108:109], v[106:107], 0, s[2:3]
	v_lshl_add_u64 v[110:111], v[108:109], 0, s[2:3]
	v_mov_b32_e32 v112, 0
	v_mov_b32_e32 v113, 0
	v_mov_b32_e32 v114, 0
	v_mov_b32_e32 v115, 0
	v_mov_b32_e32 v116, 0
	v_mov_b32_e32 v117, 0
	v_mov_b32_e32 v118, 0
	v_mov_b32_e32 v119, 0
	v_mov_b32_e32 v120, 0
	v_mov_b32_e32 v121, 0
	v_mov_b32_e32 v122, 0
	v_mov_b32_e32 v123, 0
	v_mov_b32_e32 v124, 0
	v_mov_b32_e32 v125, 0
	v_mov_b32_e32 v126, 0
	v_mov_b32_e32 v127, 0
	s_and_saveexec_b64 s[46:47], s[6:7]
	global_load_dword v112, v[80:81], off
	global_load_dword v113, v[82:83], off
	global_load_dword v114, v[84:85], off
	global_load_dword v115, v[86:87], off
	global_load_dword v116, v[88:89], off
	global_load_dword v117, v[90:91], off
	global_load_dword v118, v[92:93], off
	global_load_dword v119, v[94:95], off
	global_load_dword v120, v[96:97], off
	global_load_dword v121, v[98:99], off
	global_load_dword v122, v[100:101], off
	global_load_dword v123, v[102:103], off
	global_load_dword v124, v[104:105], off
	global_load_dword v125, v[106:107], off
	global_load_dword v126, v[108:109], off
	global_load_dword v127, v[110:111], off
	s_or_b64 exec, exec, s[46:47]
	s_andn2_b64 vcc, exec, s[44:45]
	s_cbranch_vccnz .Ltr_noscale
	v_mov_b32_e32 v76, v11
	v_ashrrev_i32_e32 v77, 31, v11
	v_lshl_add_u64 v[76:77], v[76:77], 2, s[12:13]
	global_load_dword v128, v[76:77], off
	global_load_dword v129, v[76:77], off offset:16
	global_load_dword v130, v[76:77], off offset:32
	global_load_dword v131, v[76:77], off offset:48
	global_load_dword v132, v[76:77], off offset:64
	global_load_dword v133, v[76:77], off offset:80
	global_load_dword v134, v[76:77], off offset:96
	global_load_dword v135, v[76:77], off offset:112
	global_load_dword v136, v[76:77], off offset:128
	global_load_dword v137, v[76:77], off offset:144
	global_load_dword v138, v[76:77], off offset:160
	global_load_dword v139, v[76:77], off offset:176
	global_load_dword v140, v[76:77], off offset:192
	global_load_dword v141, v[76:77], off offset:208
	global_load_dword v142, v[76:77], off offset:224
	global_load_dword v143, v[76:77], off offset:240
	s_waitcnt vmcnt(0)
	v_mul_f32_e32 v112, v112, v128
	v_mul_f32_e32 v113, v113, v129
	v_mul_f32_e32 v114, v114, v130
	v_mul_f32_e32 v115, v115, v131
	v_mul_f32_e32 v116, v116, v132
	v_mul_f32_e32 v117, v117, v133
	v_mul_f32_e32 v118, v118, v134
	v_mul_f32_e32 v119, v119, v135
	v_mul_f32_e32 v120, v120, v136
	v_mul_f32_e32 v121, v121, v137
	v_mul_f32_e32 v122, v122, v138
	v_mul_f32_e32 v123, v123, v139
	v_mul_f32_e32 v124, v124, v140
	v_mul_f32_e32 v125, v125, v141
	v_mul_f32_e32 v126, v126, v142
	v_mul_f32_e32 v127, v127, v143
.Ltr_noscale:
	s_waitcnt vmcnt(0)
	ds_write_b32 v10, v112
	ds_write_b32 v10, v113 offset:1040
	ds_write_b32 v10, v114 offset:2080
	ds_write_b32 v10, v115 offset:3120
	ds_write_b32 v10, v116 offset:4160
	ds_write_b32 v10, v117 offset:5200
	ds_write_b32 v10, v118 offset:6240
	ds_write_b32 v10, v119 offset:7280
	ds_write_b32 v10, v120 offset:8320
	ds_write_b32 v10, v121 offset:9360
	ds_write_b32 v10, v122 offset:10400
	ds_write_b32 v10, v123 offset:11440
	ds_write_b32 v10, v124 offset:12480
	ds_write_b32 v10, v125 offset:13520
	ds_write_b32 v10, v126 offset:14560
	ds_write_b32 v10, v127 offset:15600
